# grid barrier: 16th arriver of each XCD issues an early non-blocking buffer_wbl2 (B, D, I barriers) so the last arriver's write-back is shorter
# baseline (speedup 1.0000x reference)
.LBB0_960:
	s_or_b64 exec, exec, s[6:7]
	v_cvt_f32_u32_e32 v4, v2
	s_waitcnt vmcnt(0)
	buffer_inv sc1
	v_readfirstlane_b32 s4, v3
	v_sub_u32_e32 v3, 0, v2
	v_rcp_iflag_f32_e32 v4, v4
	v_add_u32_e32 v5, s4, v1
	v_mul_f32_e32 v4, 0x4f7ffffe, v4
	v_cvt_u32_f32_e32 v4, v4
	v_mul_lo_u32 v1, v3, v4
	v_mul_hi_u32 v1, v4, v1
	v_add_u32_e32 v1, v4, v1
	v_mul_hi_u32 v1, v5, v1
	v_mul_lo_u32 v3, v1, v2
	v_sub_u32_e32 v3, v5, v3
	v_add_u32_e32 v4, 1, v1
	v_cmp_ge_u32_e32 vcc, v3, v2
	s_nop 1
	v_cndmask_b32_e32 v1, v1, v4, vcc
	v_sub_u32_e32 v4, v3, v2
	v_cndmask_b32_e32 v3, v3, v4, vcc
	v_add_u32_e32 v4, 1, v1
	v_cmp_ge_u32_e32 vcc, v3, v2
	v_add_u32_e32 v3, 1, v5
	s_nop 0
	v_cndmask_b32_e32 v1, v1, v4, vcc
	v_mul_lo_u32 v4, v2, v1
	v_add_u32_e32 v2, v4, v2
	v_cmp_ne_u32_e32 vcc, v3, v2
	s_and_saveexec_b64 s[4:5], vcc
	s_xor_b64 s[4:5], exec, s[4:5]
	s_cbranch_execz .LBB0_974
	s_add_i32 s66, s22, 0x900
	s_lshl_b64 s[6:7], s[66:67], 2
	s_add_u32 s8, s2, s6
	s_addc_u32 s9, s3, s7
	s_waitcnt lgkmcnt(0)
	v_sub_u32_e32 v0, v2, v3
	v_cmp_eq_u32_e32 vcc, 16, v0
	s_cbranch_vccz .Lmy_ewb_2
	buffer_wbl2 sc1
.Lmy_ewb_2:
	global_load_dword v0, v65, s[8:9] sc1
	s_waitcnt vmcnt(0)
	v_cmp_eq_u32_e32 vcc, v0, v1
	s_and_saveexec_b64 s[6:7], vcc
	s_cbranch_execz .LBB0_973
	s_mov_b32 s20, 1
	s_mov_b64 s[10:11], 0
	s_branch .LBB0_964

.LBB0_2450:
	s_or_b64 exec, exec, s[10:11]
	v_cvt_f32_u32_e32 v4, v2
	s_waitcnt vmcnt(0)
	buffer_inv sc1
	v_readfirstlane_b32 s8, v3
	v_sub_u32_e32 v3, 0, v2
	v_rcp_iflag_f32_e32 v4, v4
	v_add_u32_e32 v5, s8, v1
	v_mul_f32_e32 v4, 0x4f7ffffe, v4
	v_cvt_u32_f32_e32 v4, v4
	v_mul_lo_u32 v1, v3, v4
	v_mul_hi_u32 v1, v4, v1
	v_add_u32_e32 v1, v4, v1
	v_mul_hi_u32 v1, v5, v1
	v_mul_lo_u32 v3, v1, v2
	v_sub_u32_e32 v3, v5, v3
	v_add_u32_e32 v4, 1, v1
	v_cmp_ge_u32_e32 vcc, v3, v2
	s_nop 1
	v_cndmask_b32_e32 v1, v1, v4, vcc
	v_sub_u32_e32 v4, v3, v2
	v_cndmask_b32_e32 v3, v3, v4, vcc
	v_add_u32_e32 v4, 1, v1
	v_cmp_ge_u32_e32 vcc, v3, v2
	v_add_u32_e32 v3, 1, v5
	s_nop 0
	v_cndmask_b32_e32 v1, v1, v4, vcc
	v_mul_lo_u32 v4, v2, v1
	v_add_u32_e32 v2, v4, v2
	v_cmp_ne_u32_e32 vcc, v3, v2
	s_and_saveexec_b64 s[8:9], vcc
	s_xor_b64 s[8:9], exec, s[8:9]
	s_cbranch_execz .LBB0_2464
	s_add_i32 s66, s26, 0x900
	s_lshl_b64 s[10:11], s[66:67], 2
	s_add_u32 s12, s6, s10
	s_addc_u32 s13, s7, s11
	s_waitcnt lgkmcnt(0)
	v_sub_u32_e32 v0, v2, v3
	v_cmp_eq_u32_e32 vcc, 16, v0
	s_cbranch_vccz .Lmy_ewb_6
	buffer_wbl2 sc1
.Lmy_ewb_6:
	global_load_dword v0, v65, s[12:13] sc1
	s_waitcnt vmcnt(0)
	v_cmp_eq_u32_e32 vcc, v0, v1
	s_and_saveexec_b64 s[10:11], vcc
	s_cbranch_execz .LBB0_2463
	s_mov_b32 s24, 1
	s_mov_b64 s[14:15], 0
	s_branch .LBB0_2454
